# q8 + stored-coefficient loads of the RG-LRU forward path issued together (5 in flight)
# speedup vs baseline: 1.0404x; 1.0045x over previous
; __device__ __forceinline__ float h2f_bits(unsigned b) { return (float)__builtin_bit_cast(_Float16, (unsigned short)(b & 0xffffu)); }
; __device__ void odd_tiles(int tid_, int bid_, int nblk_, const Params& p, int oi, int mode, bool skip_ctx, char* smem) {
;     ...
;       if (mode == 1 && d == 0) {
; #pragma unroll
;         for (int i = 0; i < 5; ++i) {
;           int e = tid + i * 256, t = e / 40, c4 = (e % 40) * 4;
;           const uint4 abq = *(const uint4*)(abrow + (size_t)t * DC + c4);
;           unsigned wv[4] = {abq.x, abq.y, abq.z, abq.w};
;           float av[4], bv4[4];
; #pragma unroll
;           for (int q = 0; q < 4; ++q) { av[q] = __expf(h2f_bits(wv[q])); bv4[q] = h2f_bits(wv[q] >> 16); }
;           *(float4*)(sA + t * 160 + c4) = make_float4(av[0], av[1], av[2], av[3]);
;           *(float4*)(sB + t * 160 + c4) = make_float4(bv4[0], bv4[1], bv4[2], bv4[3]);
;         }
.LBB0_159:
	s_andn2_b64 vcc, exec, s[20:21]
	s_cbranch_vccnz .LBB0_161
	global_load_dwordx4 v[22:25], v[168:169], off
	global_load_dwordx4 v[30:33], v[170:171], off
	global_load_dwordx4 v[34:37], v[172:173], off
	global_load_dwordx4 v[38:41], v[174:175], off
	global_load_dwordx4 v[42:45], v[176:177], off
	s_waitcnt vmcnt(4)
	v_cvt_f32_f16_e32 v26, v22
	v_cvt_f32_f16_e32 v27, v23
	v_cvt_f32_f16_e32 v28, v24
	v_cvt_f32_f16_e32 v29, v25
	v_mul_f32_e32 v26, 0x3fb8aa3b, v26
	v_mul_f32_e32 v27, 0x3fb8aa3b, v27
	v_mul_f32_e32 v28, 0x3fb8aa3b, v28
	v_mul_f32_e32 v29, 0x3fb8aa3b, v29
	v_exp_f32_e32 v26, v26
	v_exp_f32_e32 v27, v27
	v_exp_f32_e32 v28, v28
	v_exp_f32_e32 v29, v29
	v_cvt_f32_f16_sdwa v23, v23 dst_sel:DWORD dst_unused:UNUSED_PAD src0_sel:WORD_1
	v_cvt_f32_f16_sdwa v22, v22 dst_sel:DWORD dst_unused:UNUSED_PAD src0_sel:WORD_1
	v_cvt_f32_f16_sdwa v25, v25 dst_sel:DWORD dst_unused:UNUSED_PAD src0_sel:WORD_1
	v_cvt_f32_f16_sdwa v24, v24 dst_sel:DWORD dst_unused:UNUSED_PAD src0_sel:WORD_1
	ds_write_b128 v189, v[26:29] offset:10752
	ds_write_b128 v189, v[22:25] offset:31232
	s_waitcnt vmcnt(3)
	v_cvt_f32_f16_e32 v26, v30
	v_cvt_f32_f16_e32 v27, v31
	v_cvt_f32_f16_e32 v28, v32
	v_cvt_f32_f16_e32 v29, v33
	v_mul_f32_e32 v26, 0x3fb8aa3b, v26
	v_mul_f32_e32 v27, 0x3fb8aa3b, v27
	v_mul_f32_e32 v28, 0x3fb8aa3b, v28
	v_mul_f32_e32 v29, 0x3fb8aa3b, v29
	v_exp_f32_e32 v26, v26
	v_exp_f32_e32 v27, v27
	v_exp_f32_e32 v28, v28
	v_exp_f32_e32 v29, v29
	v_cvt_f32_f16_sdwa v31, v31 dst_sel:DWORD dst_unused:UNUSED_PAD src0_sel:WORD_1
	v_cvt_f32_f16_sdwa v30, v30 dst_sel:DWORD dst_unused:UNUSED_PAD src0_sel:WORD_1
	v_cvt_f32_f16_sdwa v33, v33 dst_sel:DWORD dst_unused:UNUSED_PAD src0_sel:WORD_1
	v_cvt_f32_f16_sdwa v32, v32 dst_sel:DWORD dst_unused:UNUSED_PAD src0_sel:WORD_1
	ds_write_b128 v190, v[26:29] offset:10752
	ds_write_b128 v190, v[30:33] offset:31232
	s_waitcnt vmcnt(2)
	v_cvt_f32_f16_e32 v26, v34
	v_cvt_f32_f16_e32 v27, v35
	v_cvt_f32_f16_e32 v28, v36
	v_cvt_f32_f16_e32 v29, v37
	v_mul_f32_e32 v26, 0x3fb8aa3b, v26
	v_mul_f32_e32 v27, 0x3fb8aa3b, v27
	v_mul_f32_e32 v28, 0x3fb8aa3b, v28
	v_mul_f32_e32 v29, 0x3fb8aa3b, v29
	v_exp_f32_e32 v26, v26
	v_exp_f32_e32 v27, v27
	v_exp_f32_e32 v28, v28
	v_exp_f32_e32 v29, v29
	v_cvt_f32_f16_sdwa v35, v35 dst_sel:DWORD dst_unused:UNUSED_PAD src0_sel:WORD_1
	v_cvt_f32_f16_sdwa v34, v34 dst_sel:DWORD dst_unused:UNUSED_PAD src0_sel:WORD_1
	v_cvt_f32_f16_sdwa v37, v37 dst_sel:DWORD dst_unused:UNUSED_PAD src0_sel:WORD_1
	v_cvt_f32_f16_sdwa v36, v36 dst_sel:DWORD dst_unused:UNUSED_PAD src0_sel:WORD_1
	ds_write_b128 v191, v[26:29] offset:10752
	ds_write_b128 v191, v[34:37] offset:31232
	s_waitcnt vmcnt(1)
	v_cvt_f32_f16_e32 v26, v38
	v_cvt_f32_f16_e32 v27, v39
	v_cvt_f32_f16_e32 v28, v40
	v_cvt_f32_f16_e32 v29, v41
	v_mul_f32_e32 v26, 0x3fb8aa3b, v26
	v_mul_f32_e32 v27, 0x3fb8aa3b, v27
	v_mul_f32_e32 v28, 0x3fb8aa3b, v28
	v_mul_f32_e32 v29, 0x3fb8aa3b, v29
	v_exp_f32_e32 v26, v26
	v_exp_f32_e32 v27, v27
	v_exp_f32_e32 v28, v28
	v_exp_f32_e32 v29, v29
	v_cvt_f32_f16_sdwa v39, v39 dst_sel:DWORD dst_unused:UNUSED_PAD src0_sel:WORD_1
	v_cvt_f32_f16_sdwa v38, v38 dst_sel:DWORD dst_unused:UNUSED_PAD src0_sel:WORD_1
	v_cvt_f32_f16_sdwa v41, v41 dst_sel:DWORD dst_unused:UNUSED_PAD src0_sel:WORD_1
	v_cvt_f32_f16_sdwa v40, v40 dst_sel:DWORD dst_unused:UNUSED_PAD src0_sel:WORD_1
	ds_write_b128 v234, v[26:29] offset:10752
	ds_write_b128 v234, v[38:41] offset:31232
	s_waitcnt vmcnt(0)
	v_cvt_f32_f16_e32 v26, v42
	v_cvt_f32_f16_e32 v27, v43
	v_cvt_f32_f16_e32 v28, v44
	v_cvt_f32_f16_e32 v29, v45
	v_mul_f32_e32 v26, 0x3fb8aa3b, v26
	v_mul_f32_e32 v27, 0x3fb8aa3b, v27
	v_mul_f32_e32 v28, 0x3fb8aa3b, v28
	v_mul_f32_e32 v29, 0x3fb8aa3b, v29
	v_exp_f32_e32 v26, v26
	v_exp_f32_e32 v27, v27
	v_exp_f32_e32 v28, v28
	v_exp_f32_e32 v29, v29
	v_cvt_f32_f16_sdwa v43, v43 dst_sel:DWORD dst_unused:UNUSED_PAD src0_sel:WORD_1
	v_cvt_f32_f16_sdwa v42, v42 dst_sel:DWORD dst_unused:UNUSED_PAD src0_sel:WORD_1
	v_cvt_f32_f16_sdwa v45, v45 dst_sel:DWORD dst_unused:UNUSED_PAD src0_sel:WORD_1
	v_cvt_f32_f16_sdwa v44, v44 dst_sel:DWORD dst_unused:UNUSED_PAD src0_sel:WORD_1
	ds_write_b128 v235, v[26:29] offset:10752
	ds_write_b128 v235, v[42:45] offset:31232
